# all 6 K-loops in 4 double-length phases (incl. up and w_o/down with the half-unit skip around the merged ai=1 MFMA group) + static prio for waves 4-7
# speedup vs baseline: 1.0263x; 1.0023x over previous
.LBB0_66:
	v_or_b32_e32 v142, 0x10000, v140
	v_add_u32_e32 v146, 0x10400, v140
	v_add_u32_e32 v150, 0x10800, v140
	v_add_u32_e32 v154, 0x10c00, v140
	ds_read_b128 v[142:145], v142
	ds_read_b128 v[146:149], v146
	ds_read_b128 v[150:153], v150
	ds_read_b128 v[154:157], v154
	s_add_u32 s42, s40, 0xfffc0080
	s_addc_u32 s43, s41, -1
	s_cmp_eq_u32 s96, 12
	s_cselect_b32 s45, s31, s43
	s_cselect_b32 s44, s80, s42
	s_cselect_b32 s43, s29, s27
	s_cselect_b32 s42, vcc_lo, s26
	s_mov_b32 m0, s69
	v_lshl_add_u64 v[182:183], s[40:41], 0, v[134:135]
	ds_read_b128 v[158:161], v139
	ds_read_b128 v[162:165], v139 offset:1024
	ds_read_b128 v[166:169], v139 offset:2048
	ds_read_b128 v[170:173], v139 offset:3072
	ds_read_b128 v[174:177], v139 offset:4096
	ds_read_b128 v[178:181], v139 offset:5120
	ds_read_b128 v[186:189], v139 offset:6144
	ds_read_b128 v[194:197], v139 offset:7168
	global_load_lds_dwordx4 v[182:183], off
	v_lshl_add_u64 v[182:183], s[40:41], 0, v[136:137]
	s_mov_b32 m0, s70
	s_nop 0
	global_load_lds_dwordx4 v[182:183], off
	v_or_b32_e32 v182, 0x14000, v140
	v_add_u32_e32 v183, 0x14400, v140
	ds_read_b128 v[198:201], v182
	ds_read_b128 v[202:205], v183
	v_add_u32_e32 v182, 0x14800, v140
	v_add_u32_e32 v183, 0x14c00, v140
	ds_read_b128 v[206:209], v182
	ds_read_b128 v[210:213], v183
	s_waitcnt vmcnt(8) lgkmcnt(0)
	s_barrier
	v_mfma_f32_16x16x32_bf16 v[124:127], v[142:145], v[158:161], v[124:127]
	v_mfma_f32_16x16x32_bf16 v[116:119], v[150:153], v[158:161], v[116:119]
	v_mfma_f32_16x16x32_bf16 v[108:111], v[142:145], v[166:169], v[108:111]
	v_mfma_f32_16x16x32_bf16 v[100:103], v[150:153], v[166:169], v[100:103]
	v_mfma_f32_16x16x32_bf16 v[92:95], v[142:145], v[174:177], v[92:95]
	v_mfma_f32_16x16x32_bf16 v[84:87], v[150:153], v[174:177], v[84:87]
	v_mfma_f32_16x16x32_bf16 v[76:79], v[142:145], v[186:189], v[76:79]
	v_mfma_f32_16x16x32_bf16 v[68:71], v[150:153], v[186:189], v[68:71]
	v_mfma_f32_16x16x32_bf16 v[124:127], v[146:149], v[162:165], v[124:127]
	v_mfma_f32_16x16x32_bf16 v[116:119], v[154:157], v[162:165], v[116:119]
	v_mfma_f32_16x16x32_bf16 v[108:111], v[146:149], v[170:173], v[108:111]
	v_mfma_f32_16x16x32_bf16 v[100:103], v[154:157], v[170:173], v[100:103]
	v_mfma_f32_16x16x32_bf16 v[92:95], v[146:149], v[178:181], v[92:95]
	v_mfma_f32_16x16x32_bf16 v[84:87], v[154:157], v[178:181], v[84:87]
	v_mfma_f32_16x16x32_bf16 v[76:79], v[146:149], v[194:197], v[76:79]
	v_mfma_f32_16x16x32_bf16 v[68:71], v[154:157], v[194:197], v[68:71]
	v_mfma_f32_16x16x32_bf16 v[120:123], v[198:201], v[158:161], v[120:123]
	v_mfma_f32_16x16x32_bf16 v[112:115], v[206:209], v[158:161], v[112:115]
	v_mfma_f32_16x16x32_bf16 v[104:107], v[198:201], v[166:169], v[104:107]
	v_mfma_f32_16x16x32_bf16 v[96:99], v[206:209], v[166:169], v[96:99]
	v_mfma_f32_16x16x32_bf16 v[88:91], v[198:201], v[174:177], v[88:91]
	v_mfma_f32_16x16x32_bf16 v[80:83], v[206:209], v[174:177], v[80:83]
	v_mfma_f32_16x16x32_bf16 v[72:75], v[198:201], v[186:189], v[72:75]
	v_mfma_f32_16x16x32_bf16 v[64:67], v[206:209], v[186:189], v[64:67]
	v_mfma_f32_16x16x32_bf16 v[120:123], v[202:205], v[162:165], v[120:123]
	v_mfma_f32_16x16x32_bf16 v[112:115], v[210:213], v[162:165], v[112:115]
	v_mfma_f32_16x16x32_bf16 v[104:107], v[202:205], v[170:173], v[104:107]
	v_mfma_f32_16x16x32_bf16 v[96:99], v[210:213], v[170:173], v[96:99]
	v_mfma_f32_16x16x32_bf16 v[88:91], v[202:205], v[178:181], v[88:91]
	v_mfma_f32_16x16x32_bf16 v[80:83], v[210:213], v[178:181], v[80:83]
	v_mfma_f32_16x16x32_bf16 v[72:75], v[202:205], v[194:197], v[72:75]
	v_mfma_f32_16x16x32_bf16 v[64:67], v[210:213], v[194:197], v[64:67]
	s_barrier
	s_mov_b32 m0, s39
	v_lshl_add_u64 v[182:183], s[42:43], 0, v[184:185]
	global_load_lds_dwordx4 v[182:183], off
	v_lshl_add_u64 v[190:191], s[42:43], 0, v[128:129]
	s_mov_b32 m0, s53
	s_nop 0
	global_load_lds_dwordx4 v[190:191], off
	s_mov_b32 m0, s50
	v_lshl_add_u64 v[214:215], s[44:45], 0, v[132:133]
	ds_read_b128 v[158:161], v139 offset:16384
	ds_read_b128 v[162:165], v139 offset:17408
	ds_read_b128 v[166:169], v139 offset:18432
	ds_read_b128 v[170:173], v139 offset:19456
	ds_read_b128 v[174:177], v139 offset:20480
	ds_read_b128 v[178:181], v139 offset:21504
	ds_read_b128 v[186:189], v139 offset:22528
	ds_read_b128 v[194:197], v139 offset:23552
	global_load_lds_dwordx4 v[214:215], off
	v_lshl_add_u64 v[216:217], s[44:45], 0, v[130:131]
	s_mov_b32 m0, s54
	s_nop 0
	global_load_lds_dwordx4 v[216:217], off
	s_waitcnt vmcnt(6) lgkmcnt(0)
	s_barrier
	s_cmp_lg_u32 s100, 0
	s_cbranch_scc1 .Lmskip_66_2
	v_mfma_f32_16x16x32_bf16 v[60:63], v[142:145], v[158:161], v[60:63]
	v_mfma_f32_16x16x32_bf16 v[52:55], v[150:153], v[158:161], v[52:55]
	v_mfma_f32_16x16x32_bf16 v[44:47], v[142:145], v[166:169], v[44:47]
	v_mfma_f32_16x16x32_bf16 v[36:39], v[150:153], v[166:169], v[36:39]
	v_mfma_f32_16x16x32_bf16 v[28:31], v[142:145], v[174:177], v[28:31]
	v_mfma_f32_16x16x32_bf16 v[20:23], v[150:153], v[174:177], v[20:23]
	v_mfma_f32_16x16x32_bf16 v[12:15], v[142:145], v[186:189], v[12:15]
	v_mfma_f32_16x16x32_bf16 v[4:7], v[150:153], v[186:189], v[4:7]
	v_mfma_f32_16x16x32_bf16 v[60:63], v[146:149], v[162:165], v[60:63]
	v_mfma_f32_16x16x32_bf16 v[52:55], v[154:157], v[162:165], v[52:55]
	v_mfma_f32_16x16x32_bf16 v[44:47], v[146:149], v[170:173], v[44:47]
	v_mfma_f32_16x16x32_bf16 v[36:39], v[154:157], v[170:173], v[36:39]
	v_mfma_f32_16x16x32_bf16 v[28:31], v[146:149], v[178:181], v[28:31]
	v_mfma_f32_16x16x32_bf16 v[20:23], v[154:157], v[178:181], v[20:23]
	v_mfma_f32_16x16x32_bf16 v[12:15], v[146:149], v[194:197], v[12:15]
	v_mfma_f32_16x16x32_bf16 v[4:7], v[154:157], v[194:197], v[4:7]
	v_mfma_f32_16x16x32_bf16 v[56:59], v[198:201], v[158:161], v[56:59]
	v_mfma_f32_16x16x32_bf16 v[48:51], v[206:209], v[158:161], v[48:51]
	v_mfma_f32_16x16x32_bf16 v[40:43], v[198:201], v[166:169], v[40:43]
	v_mfma_f32_16x16x32_bf16 v[32:35], v[206:209], v[166:169], v[32:35]
	v_mfma_f32_16x16x32_bf16 v[24:27], v[198:201], v[174:177], v[24:27]
	v_mfma_f32_16x16x32_bf16 v[16:19], v[206:209], v[174:177], v[16:19]
	v_mfma_f32_16x16x32_bf16 v[8:11], v[198:201], v[186:189], v[8:11]
	v_mfma_f32_16x16x32_bf16 v[0:3], v[206:209], v[186:189], v[0:3]
	v_mfma_f32_16x16x32_bf16 v[56:59], v[202:205], v[162:165], v[56:59]
	v_mfma_f32_16x16x32_bf16 v[48:51], v[210:213], v[162:165], v[48:51]
	v_mfma_f32_16x16x32_bf16 v[40:43], v[202:205], v[170:173], v[40:43]
	v_mfma_f32_16x16x32_bf16 v[32:35], v[210:213], v[170:173], v[32:35]
	v_mfma_f32_16x16x32_bf16 v[24:27], v[202:205], v[178:181], v[24:27]
	v_mfma_f32_16x16x32_bf16 v[16:19], v[210:213], v[178:181], v[16:19]
	v_mfma_f32_16x16x32_bf16 v[8:11], v[202:205], v[194:197], v[8:11]
	v_mfma_f32_16x16x32_bf16 v[0:3], v[210:213], v[194:197], v[0:3]
.Lmskip_66_2:
	s_barrier
	s_add_u32 s66, s42, 0x40000
	s_addc_u32 s67, s43, 0
	s_mov_b32 m0, s55
	v_lshl_add_u64 v[142:143], s[66:67], 0, v[184:185]
	global_load_lds_dwordx4 v[142:143], off
	v_lshl_add_u64 v[142:143], s[66:67], 0, v[128:129]
	s_mov_b32 m0, s58
	s_nop 0
	global_load_lds_dwordx4 v[142:143], off
	v_or_b32_e32 v142, 0x18000, v140
	v_add_u32_e32 v146, 0x18400, v140
	v_add_u32_e32 v150, 0x18800, v140
	v_add_u32_e32 v154, 0x18c00, v140
	ds_read_b128 v[142:145], v142
	ds_read_b128 v[146:149], v146
	ds_read_b128 v[150:153], v150
	ds_read_b128 v[154:157], v154
	s_add_u32 s44, s44, 0x40000
	s_addc_u32 s45, s45, 0
	s_mov_b32 m0, s59
	v_lshl_add_u64 v[198:199], s[44:45], 0, v[132:133]
	ds_read_b128 v[158:161], v139 offset:32768
	ds_read_b128 v[162:165], v139 offset:33792
	ds_read_b128 v[166:169], v139 offset:34816
	ds_read_b128 v[170:173], v139 offset:35840
	ds_read_b128 v[174:177], v139 offset:36864
	ds_read_b128 v[178:181], v139 offset:37888
	ds_read_b128 v[186:189], v139 offset:38912
	ds_read_b128 v[194:197], v139 offset:39936
	global_load_lds_dwordx4 v[198:199], off
	v_lshl_add_u64 v[198:199], s[44:45], 0, v[130:131]
	s_mov_b32 m0, s60
	s_nop 0
	global_load_lds_dwordx4 v[198:199], off
	v_or_b32_e32 v192, 0x1c000, v140
	v_add_u32_e32 v202, 0x1c400, v140
	ds_read_b128 v[198:201], v192
	ds_read_b128 v[202:205], v202
	v_add_u32_e32 v192, 0x1c800, v140
	v_add_u32_e32 v210, 0x1cc00, v140
	ds_read_b128 v[206:209], v192
	ds_read_b128 v[210:213], v210
	s_waitcnt vmcnt(8) lgkmcnt(0)
	s_barrier
	v_mfma_f32_16x16x32_bf16 v[124:127], v[142:145], v[158:161], v[124:127]
	v_mfma_f32_16x16x32_bf16 v[116:119], v[150:153], v[158:161], v[116:119]
	v_mfma_f32_16x16x32_bf16 v[108:111], v[142:145], v[166:169], v[108:111]
	v_mfma_f32_16x16x32_bf16 v[100:103], v[150:153], v[166:169], v[100:103]
	v_mfma_f32_16x16x32_bf16 v[92:95], v[142:145], v[174:177], v[92:95]
	v_mfma_f32_16x16x32_bf16 v[84:87], v[150:153], v[174:177], v[84:87]
	v_mfma_f32_16x16x32_bf16 v[76:79], v[142:145], v[186:189], v[76:79]
	v_mfma_f32_16x16x32_bf16 v[68:71], v[150:153], v[186:189], v[68:71]
	v_mfma_f32_16x16x32_bf16 v[124:127], v[146:149], v[162:165], v[124:127]
	v_mfma_f32_16x16x32_bf16 v[116:119], v[154:157], v[162:165], v[116:119]
	v_mfma_f32_16x16x32_bf16 v[108:111], v[146:149], v[170:173], v[108:111]
	v_mfma_f32_16x16x32_bf16 v[100:103], v[154:157], v[170:173], v[100:103]
	v_mfma_f32_16x16x32_bf16 v[92:95], v[146:149], v[178:181], v[92:95]
	v_mfma_f32_16x16x32_bf16 v[84:87], v[154:157], v[178:181], v[84:87]
	v_mfma_f32_16x16x32_bf16 v[76:79], v[146:149], v[194:197], v[76:79]
	v_mfma_f32_16x16x32_bf16 v[68:71], v[154:157], v[194:197], v[68:71]
	v_mfma_f32_16x16x32_bf16 v[120:123], v[198:201], v[158:161], v[120:123]
	v_mfma_f32_16x16x32_bf16 v[112:115], v[206:209], v[158:161], v[112:115]
	v_mfma_f32_16x16x32_bf16 v[104:107], v[198:201], v[166:169], v[104:107]
	v_mfma_f32_16x16x32_bf16 v[96:99], v[206:209], v[166:169], v[96:99]
	v_mfma_f32_16x16x32_bf16 v[88:91], v[198:201], v[174:177], v[88:91]
	v_mfma_f32_16x16x32_bf16 v[80:83], v[206:209], v[174:177], v[80:83]
	v_mfma_f32_16x16x32_bf16 v[72:75], v[198:201], v[186:189], v[72:75]
	v_mfma_f32_16x16x32_bf16 v[64:67], v[206:209], v[186:189], v[64:67]
	v_mfma_f32_16x16x32_bf16 v[120:123], v[202:205], v[162:165], v[120:123]
	v_mfma_f32_16x16x32_bf16 v[112:115], v[210:213], v[162:165], v[112:115]
	v_mfma_f32_16x16x32_bf16 v[104:107], v[202:205], v[170:173], v[104:107]
	v_mfma_f32_16x16x32_bf16 v[96:99], v[210:213], v[170:173], v[96:99]
	v_mfma_f32_16x16x32_bf16 v[88:91], v[202:205], v[178:181], v[88:91]
	v_mfma_f32_16x16x32_bf16 v[80:83], v[210:213], v[178:181], v[80:83]
	v_mfma_f32_16x16x32_bf16 v[72:75], v[202:205], v[194:197], v[72:75]
	v_mfma_f32_16x16x32_bf16 v[64:67], v[210:213], v[194:197], v[64:67]
	s_barrier
	s_mov_b32 m0, s33
	v_lshl_add_u64 v[182:183], v[182:183], 0, s[24:25]
	global_load_lds_dwordx4 v[182:183], off
	v_lshl_add_u64 v[182:183], v[190:191], 0, s[24:25]
	s_mov_b32 m0, s61
	s_nop 0
	global_load_lds_dwordx4 v[182:183], off
	s_mov_b32 m0, s62
	v_lshl_add_u64 v[182:183], v[214:215], 0, s[24:25]
	ds_read_b128 v[158:161], v139 offset:49152
	ds_read_b128 v[162:165], v139 offset:50176
	ds_read_b128 v[166:169], v139 offset:51200
	ds_read_b128 v[170:173], v139 offset:52224
	ds_read_b128 v[174:177], v139 offset:53248
	ds_read_b128 v[178:181], v139 offset:54272
	ds_read_b128 v[186:189], v139 offset:55296
	ds_read_b128 v[194:197], v139 offset:56320
	global_load_lds_dwordx4 v[182:183], off
	v_lshl_add_u64 v[182:183], v[216:217], 0, s[24:25]
	s_mov_b32 m0, s63
	s_nop 0
	global_load_lds_dwordx4 v[182:183], off
	s_waitcnt vmcnt(6) lgkmcnt(0)
	s_barrier
	s_cmp_lg_u32 s100, 0
	s_cbranch_scc1 .Lmskip_66_6
	v_mfma_f32_16x16x32_bf16 v[60:63], v[142:145], v[158:161], v[60:63]
	v_mfma_f32_16x16x32_bf16 v[52:55], v[150:153], v[158:161], v[52:55]
	v_mfma_f32_16x16x32_bf16 v[44:47], v[142:145], v[166:169], v[44:47]
	v_mfma_f32_16x16x32_bf16 v[36:39], v[150:153], v[166:169], v[36:39]
	v_mfma_f32_16x16x32_bf16 v[28:31], v[142:145], v[174:177], v[28:31]
	v_mfma_f32_16x16x32_bf16 v[20:23], v[150:153], v[174:177], v[20:23]
	v_mfma_f32_16x16x32_bf16 v[12:15], v[142:145], v[186:189], v[12:15]
	v_mfma_f32_16x16x32_bf16 v[4:7], v[150:153], v[186:189], v[4:7]
	v_mfma_f32_16x16x32_bf16 v[60:63], v[146:149], v[162:165], v[60:63]
	v_mfma_f32_16x16x32_bf16 v[52:55], v[154:157], v[162:165], v[52:55]
	v_mfma_f32_16x16x32_bf16 v[44:47], v[146:149], v[170:173], v[44:47]
	v_mfma_f32_16x16x32_bf16 v[36:39], v[154:157], v[170:173], v[36:39]
	v_mfma_f32_16x16x32_bf16 v[28:31], v[146:149], v[178:181], v[28:31]
	v_mfma_f32_16x16x32_bf16 v[20:23], v[154:157], v[178:181], v[20:23]
	v_mfma_f32_16x16x32_bf16 v[12:15], v[146:149], v[194:197], v[12:15]
	v_mfma_f32_16x16x32_bf16 v[4:7], v[154:157], v[194:197], v[4:7]
	v_mfma_f32_16x16x32_bf16 v[56:59], v[198:201], v[158:161], v[56:59]
	v_mfma_f32_16x16x32_bf16 v[48:51], v[206:209], v[158:161], v[48:51]
	v_mfma_f32_16x16x32_bf16 v[40:43], v[198:201], v[166:169], v[40:43]
	v_mfma_f32_16x16x32_bf16 v[32:35], v[206:209], v[166:169], v[32:35]
	v_mfma_f32_16x16x32_bf16 v[24:27], v[198:201], v[174:177], v[24:27]
	v_mfma_f32_16x16x32_bf16 v[16:19], v[206:209], v[174:177], v[16:19]
	v_mfma_f32_16x16x32_bf16 v[8:11], v[198:201], v[186:189], v[8:11]
	v_mfma_f32_16x16x32_bf16 v[0:3], v[206:209], v[186:189], v[0:3]
	v_mfma_f32_16x16x32_bf16 v[56:59], v[202:205], v[162:165], v[56:59]
	v_mfma_f32_16x16x32_bf16 v[48:51], v[210:213], v[162:165], v[48:51]
	v_mfma_f32_16x16x32_bf16 v[40:43], v[202:205], v[170:173], v[40:43]
	v_mfma_f32_16x16x32_bf16 v[32:35], v[210:213], v[170:173], v[32:35]
	v_mfma_f32_16x16x32_bf16 v[24:27], v[202:205], v[178:181], v[24:27]
	v_mfma_f32_16x16x32_bf16 v[16:19], v[210:213], v[178:181], v[16:19]
	v_mfma_f32_16x16x32_bf16 v[8:11], v[202:205], v[194:197], v[8:11]
	v_mfma_f32_16x16x32_bf16 v[0:3], v[210:213], v[194:197], v[0:3]
.Lmskip_66_6:
	s_barrier
	s_add_u32 s42, s42, 0x40080
	s_addc_u32 s43, s43, 0
	s_mov_b32 m0, s64
	v_lshl_add_u64 v[142:143], s[42:43], 0, v[184:185]
	global_load_lds_dwordx4 v[142:143], off
	v_lshl_add_u64 v[142:143], s[42:43], 0, v[128:129]
	s_mov_b32 m0, s65
	s_nop 0
	global_load_lds_dwordx4 v[142:143], off
	s_add_i32 s96, s96, 2
	s_add_u32 s40, s40, 0x100
	s_addc_u32 s41, s41, 0
	s_add_u32 s26, s26, 0x100
	s_addc_u32 s27, s27, 0
	s_cmp_gt_u32 s96, 13
	s_cbranch_scc0 .LBB0_66
	v_mul_f32_e32 v143, 0xbfb8aa3b, v124
	v_exp_f32_e32 v143, v143
	v_readlane_b32 s4, v254, 2
	v_lshl_or_b32 v144, s71, 7, v141
	v_readlane_b32 s5, v254, 3
	v_add_f32_e32 v143, 1.0, v143
	v_rcp_f32_e32 v143, v143
	v_lshl_add_u32 v142, s38, 8, v138
	s_cmp_eq_u32 s100, 2
	s_cbranch_scc0 .Luph_noshift
	v_add_u32_e32 v142, 0x80, v142

.LBB0_94:
	v_or_b32_e32 v138, 0x10000, v142
	v_add_u32_e32 v139, 0x10400, v142
	ds_read_b128 v[144:147], v138
	ds_read_b128 v[148:151], v139
	v_add_u32_e32 v138, 0x10800, v142
	s_add_i32 s71, s34, 2
	v_add_u32_e32 v139, 0x10c00, v142
	ds_read_b128 v[152:155], v138
	ds_read_b128 v[156:159], v139
	s_add_u32 s36, s30, 0x80
	s_addc_u32 s35, s31, 0
	s_cmp_eq_u32 s63, s34
	s_cselect_b32 s34, s28, s36
	s_cselect_b32 s35, s29, s35
	s_cselect_b32 s37, s1, s27
	s_cselect_b32 s36, s0, s26
	v_lshl_add_u64 v[138:139], s[30:31], 0, v[134:135]
	s_add_i32 m0, s44, 0xc000
	ds_read_b128 v[160:163], v141
	ds_read_b128 v[164:167], v141 offset:1024
	ds_read_b128 v[168:171], v141 offset:2048
	ds_read_b128 v[172:175], v141 offset:3072
	ds_read_b128 v[176:179], v141 offset:4096
	ds_read_b128 v[180:183], v141 offset:5120
	ds_read_b128 v[186:189], v141 offset:6144
	ds_read_b128 v[194:197], v141 offset:7168
	global_load_lds_dwordx4 v[138:139], off
	v_lshl_add_u64 v[138:139], s[30:31], 0, v[136:137]
	s_add_i32 m0, s44, 0xe000
	s_nop 0
	global_load_lds_dwordx4 v[138:139], off
	v_or_b32_e32 v138, 0x14000, v142
	v_add_u32_e32 v139, 0x14400, v142
	ds_read_b128 v[198:201], v138
	ds_read_b128 v[202:205], v139
	v_add_u32_e32 v138, 0x14800, v142
	v_add_u32_e32 v139, 0x14c00, v142
	ds_read_b128 v[206:209], v138
	ds_read_b128 v[210:213], v139
	s_waitcnt vmcnt(8) lgkmcnt(0)
	s_barrier
	v_mfma_f32_16x16x32_bf16 v[124:127], v[144:147], v[160:163], v[124:127]
	v_mfma_f32_16x16x32_bf16 v[120:123], v[152:155], v[160:163], v[120:123]
	v_mfma_f32_16x16x32_bf16 v[116:119], v[144:147], v[168:171], v[116:119]
	v_mfma_f32_16x16x32_bf16 v[112:115], v[152:155], v[168:171], v[112:115]
	v_mfma_f32_16x16x32_bf16 v[108:111], v[144:147], v[176:179], v[108:111]
	v_mfma_f32_16x16x32_bf16 v[104:107], v[152:155], v[176:179], v[104:107]
	v_mfma_f32_16x16x32_bf16 v[100:103], v[144:147], v[186:189], v[100:103]
	v_mfma_f32_16x16x32_bf16 v[96:99], v[152:155], v[186:189], v[96:99]
	v_mfma_f32_16x16x32_bf16 v[124:127], v[148:151], v[164:167], v[124:127]
	v_mfma_f32_16x16x32_bf16 v[120:123], v[156:159], v[164:167], v[120:123]
	v_mfma_f32_16x16x32_bf16 v[116:119], v[148:151], v[172:175], v[116:119]
	v_mfma_f32_16x16x32_bf16 v[112:115], v[156:159], v[172:175], v[112:115]
	v_mfma_f32_16x16x32_bf16 v[108:111], v[148:151], v[180:183], v[108:111]
	v_mfma_f32_16x16x32_bf16 v[104:107], v[156:159], v[180:183], v[104:107]
	v_mfma_f32_16x16x32_bf16 v[100:103], v[148:151], v[194:197], v[100:103]
	v_mfma_f32_16x16x32_bf16 v[96:99], v[156:159], v[194:197], v[96:99]
	v_mfma_f32_16x16x32_bf16 v[92:95], v[198:201], v[160:163], v[92:95]
	v_mfma_f32_16x16x32_bf16 v[88:91], v[206:209], v[160:163], v[88:91]
	v_mfma_f32_16x16x32_bf16 v[84:87], v[198:201], v[168:171], v[84:87]
	v_mfma_f32_16x16x32_bf16 v[80:83], v[206:209], v[168:171], v[80:83]
	v_mfma_f32_16x16x32_bf16 v[76:79], v[198:201], v[176:179], v[76:79]
	v_mfma_f32_16x16x32_bf16 v[72:75], v[206:209], v[176:179], v[72:75]
	v_mfma_f32_16x16x32_bf16 v[68:71], v[198:201], v[186:189], v[68:71]
	v_mfma_f32_16x16x32_bf16 v[64:67], v[206:209], v[186:189], v[64:67]
	v_mfma_f32_16x16x32_bf16 v[92:95], v[202:205], v[164:167], v[92:95]
	v_mfma_f32_16x16x32_bf16 v[88:91], v[210:213], v[164:167], v[88:91]
	v_mfma_f32_16x16x32_bf16 v[84:87], v[202:205], v[172:175], v[84:87]
	v_mfma_f32_16x16x32_bf16 v[80:83], v[210:213], v[172:175], v[80:83]
	v_mfma_f32_16x16x32_bf16 v[76:79], v[202:205], v[180:183], v[76:79]
	v_mfma_f32_16x16x32_bf16 v[72:75], v[210:213], v[180:183], v[72:75]
	v_mfma_f32_16x16x32_bf16 v[68:71], v[202:205], v[194:197], v[68:71]
	v_mfma_f32_16x16x32_bf16 v[64:67], v[210:213], v[194:197], v[64:67]
	s_barrier
	s_mov_b32 m0, s47
	v_lshl_add_u64 v[138:139], s[36:37], 0, v[184:185]
	global_load_lds_dwordx4 v[138:139], off
	v_lshl_add_u64 v[190:191], s[36:37], 0, v[128:129]
	s_mov_b32 m0, s48
	s_nop 0
	global_load_lds_dwordx4 v[190:191], off
	s_mov_b32 m0, s44
	v_lshl_add_u64 v[214:215], s[34:35], 0, v[132:133]
	ds_read_b128 v[160:163], v141 offset:16384
	ds_read_b128 v[164:167], v141 offset:17408
	ds_read_b128 v[168:171], v141 offset:18432
	ds_read_b128 v[172:175], v141 offset:19456
	ds_read_b128 v[176:179], v141 offset:20480
	ds_read_b128 v[180:183], v141 offset:21504
	ds_read_b128 v[186:189], v141 offset:22528
	ds_read_b128 v[194:197], v141 offset:23552
	global_load_lds_dwordx4 v[214:215], off
	v_lshl_add_u64 v[216:217], s[34:35], 0, v[130:131]
	s_mov_b32 m0, s49
	s_nop 0
	global_load_lds_dwordx4 v[216:217], off
	s_waitcnt vmcnt(6) lgkmcnt(0)
	s_barrier
	s_cbranch_vccnz .Lmskip_94_2
	v_mfma_f32_16x16x32_bf16 v[60:63], v[144:147], v[160:163], v[60:63]
	v_mfma_f32_16x16x32_bf16 v[56:59], v[152:155], v[160:163], v[56:59]
	v_mfma_f32_16x16x32_bf16 v[52:55], v[144:147], v[168:171], v[52:55]
	v_mfma_f32_16x16x32_bf16 v[48:51], v[152:155], v[168:171], v[48:51]
	v_mfma_f32_16x16x32_bf16 v[44:47], v[144:147], v[176:179], v[44:47]
	v_mfma_f32_16x16x32_bf16 v[40:43], v[152:155], v[176:179], v[40:43]
	v_mfma_f32_16x16x32_bf16 v[36:39], v[144:147], v[186:189], v[36:39]
	v_mfma_f32_16x16x32_bf16 v[32:35], v[152:155], v[186:189], v[32:35]
	v_mfma_f32_16x16x32_bf16 v[60:63], v[148:151], v[164:167], v[60:63]
	v_mfma_f32_16x16x32_bf16 v[56:59], v[156:159], v[164:167], v[56:59]
	v_mfma_f32_16x16x32_bf16 v[52:55], v[148:151], v[172:175], v[52:55]
	v_mfma_f32_16x16x32_bf16 v[48:51], v[156:159], v[172:175], v[48:51]
	v_mfma_f32_16x16x32_bf16 v[44:47], v[148:151], v[180:183], v[44:47]
	v_mfma_f32_16x16x32_bf16 v[40:43], v[156:159], v[180:183], v[40:43]
	v_mfma_f32_16x16x32_bf16 v[36:39], v[148:151], v[194:197], v[36:39]
	v_mfma_f32_16x16x32_bf16 v[32:35], v[156:159], v[194:197], v[32:35]
	v_mfma_f32_16x16x32_bf16 v[28:31], v[198:201], v[160:163], v[28:31]
	v_mfma_f32_16x16x32_bf16 v[24:27], v[206:209], v[160:163], v[24:27]
	v_mfma_f32_16x16x32_bf16 v[20:23], v[198:201], v[168:171], v[20:23]
	v_mfma_f32_16x16x32_bf16 v[16:19], v[206:209], v[168:171], v[16:19]
	v_mfma_f32_16x16x32_bf16 v[12:15], v[198:201], v[176:179], v[12:15]
	v_mfma_f32_16x16x32_bf16 v[8:11], v[206:209], v[176:179], v[8:11]
	v_mfma_f32_16x16x32_bf16 v[4:7], v[198:201], v[186:189], v[4:7]
	v_mfma_f32_16x16x32_bf16 v[0:3], v[206:209], v[186:189], v[0:3]
	v_mfma_f32_16x16x32_bf16 v[28:31], v[202:205], v[164:167], v[28:31]
	v_mfma_f32_16x16x32_bf16 v[24:27], v[210:213], v[164:167], v[24:27]
	v_mfma_f32_16x16x32_bf16 v[20:23], v[202:205], v[172:175], v[20:23]
	v_mfma_f32_16x16x32_bf16 v[16:19], v[210:213], v[172:175], v[16:19]
	v_mfma_f32_16x16x32_bf16 v[12:15], v[202:205], v[180:183], v[12:15]
	v_mfma_f32_16x16x32_bf16 v[8:11], v[210:213], v[180:183], v[8:11]
	v_mfma_f32_16x16x32_bf16 v[4:7], v[202:205], v[194:197], v[4:7]
	v_mfma_f32_16x16x32_bf16 v[0:3], v[210:213], v[194:197], v[0:3]
.Lmskip_94_2:
	s_barrier
	s_add_u32 s36, s36, s88
	s_addc_u32 s37, s37, 0
	s_mov_b32 m0, s50
	v_lshl_add_u64 v[230:231], s[36:37], 0, v[184:185]
	global_load_lds_dwordx4 v[230:231], off
	v_lshl_add_u64 v[232:233], s[36:37], 0, v[128:129]
	s_mov_b32 m0, s51
	s_nop 0
	global_load_lds_dwordx4 v[232:233], off
	v_or_b32_e32 v144, 0x18000, v142
	v_add_u32_e32 v148, 0x18400, v142
	v_add_u32_e32 v152, 0x18800, v142
	v_add_u32_e32 v156, 0x18c00, v142
	ds_read_b128 v[144:147], v144
	ds_read_b128 v[148:151], v148
	ds_read_b128 v[152:155], v152
	ds_read_b128 v[156:159], v156
	s_add_u32 s34, s34, s88
	s_addc_u32 s35, s35, 0
	s_mov_b32 m0, s52
	v_lshl_add_u64 v[198:199], s[34:35], 0, v[132:133]
	ds_read_b128 v[160:163], v141 offset:32768
	ds_read_b128 v[164:167], v141 offset:33792
	ds_read_b128 v[168:171], v141 offset:34816
	ds_read_b128 v[172:175], v141 offset:35840
	ds_read_b128 v[176:179], v141 offset:36864
	ds_read_b128 v[180:183], v141 offset:37888
	ds_read_b128 v[186:189], v141 offset:38912
	ds_read_b128 v[194:197], v141 offset:39936
	global_load_lds_dwordx4 v[198:199], off
	v_lshl_add_u64 v[198:199], s[34:35], 0, v[130:131]
	s_mov_b32 m0, s53
	s_nop 0
	global_load_lds_dwordx4 v[198:199], off
	v_or_b32_e32 v192, 0x1c000, v142
	v_add_u32_e32 v202, 0x1c400, v142
	ds_read_b128 v[198:201], v192
	ds_read_b128 v[202:205], v202
	v_add_u32_e32 v192, 0x1c800, v142
	v_add_u32_e32 v210, 0x1cc00, v142
	ds_read_b128 v[206:209], v192
	ds_read_b128 v[210:213], v210
	s_waitcnt vmcnt(8) lgkmcnt(0)
	s_barrier
	v_mfma_f32_16x16x32_bf16 v[124:127], v[144:147], v[160:163], v[124:127]
	v_mfma_f32_16x16x32_bf16 v[120:123], v[152:155], v[160:163], v[120:123]
	v_mfma_f32_16x16x32_bf16 v[116:119], v[144:147], v[168:171], v[116:119]
	v_mfma_f32_16x16x32_bf16 v[112:115], v[152:155], v[168:171], v[112:115]
	v_mfma_f32_16x16x32_bf16 v[108:111], v[144:147], v[176:179], v[108:111]
	v_mfma_f32_16x16x32_bf16 v[104:107], v[152:155], v[176:179], v[104:107]
	v_mfma_f32_16x16x32_bf16 v[100:103], v[144:147], v[186:189], v[100:103]
	v_mfma_f32_16x16x32_bf16 v[96:99], v[152:155], v[186:189], v[96:99]
	v_mfma_f32_16x16x32_bf16 v[124:127], v[148:151], v[164:167], v[124:127]
	v_mfma_f32_16x16x32_bf16 v[120:123], v[156:159], v[164:167], v[120:123]
	v_mfma_f32_16x16x32_bf16 v[116:119], v[148:151], v[172:175], v[116:119]
	v_mfma_f32_16x16x32_bf16 v[112:115], v[156:159], v[172:175], v[112:115]
	v_mfma_f32_16x16x32_bf16 v[108:111], v[148:151], v[180:183], v[108:111]
	v_mfma_f32_16x16x32_bf16 v[104:107], v[156:159], v[180:183], v[104:107]
	v_mfma_f32_16x16x32_bf16 v[100:103], v[148:151], v[194:197], v[100:103]
	v_mfma_f32_16x16x32_bf16 v[96:99], v[156:159], v[194:197], v[96:99]
	v_mfma_f32_16x16x32_bf16 v[92:95], v[198:201], v[160:163], v[92:95]
	v_mfma_f32_16x16x32_bf16 v[88:91], v[206:209], v[160:163], v[88:91]
	v_mfma_f32_16x16x32_bf16 v[84:87], v[198:201], v[168:171], v[84:87]
	v_mfma_f32_16x16x32_bf16 v[80:83], v[206:209], v[168:171], v[80:83]
	v_mfma_f32_16x16x32_bf16 v[76:79], v[198:201], v[176:179], v[76:79]
	v_mfma_f32_16x16x32_bf16 v[72:75], v[206:209], v[176:179], v[72:75]
	v_mfma_f32_16x16x32_bf16 v[68:71], v[198:201], v[186:189], v[68:71]
	v_mfma_f32_16x16x32_bf16 v[64:67], v[206:209], v[186:189], v[64:67]
	v_mfma_f32_16x16x32_bf16 v[92:95], v[202:205], v[164:167], v[92:95]
	v_mfma_f32_16x16x32_bf16 v[88:91], v[210:213], v[164:167], v[88:91]
	v_mfma_f32_16x16x32_bf16 v[84:87], v[202:205], v[172:175], v[84:87]
	v_mfma_f32_16x16x32_bf16 v[80:83], v[210:213], v[172:175], v[80:83]
	v_mfma_f32_16x16x32_bf16 v[76:79], v[202:205], v[180:183], v[76:79]
	v_mfma_f32_16x16x32_bf16 v[72:75], v[210:213], v[180:183], v[72:75]
	v_mfma_f32_16x16x32_bf16 v[68:71], v[202:205], v[194:197], v[68:71]
	v_mfma_f32_16x16x32_bf16 v[64:67], v[210:213], v[194:197], v[64:67]
	s_barrier
	s_mov_b32 m0, s55
	v_lshl_add_u64 v[138:139], v[138:139], 0, s[24:25]
	global_load_lds_dwordx4 v[138:139], off
	v_lshl_add_u64 v[138:139], v[190:191], 0, s[24:25]
	s_mov_b32 m0, s58
	s_nop 0
	global_load_lds_dwordx4 v[138:139], off
	s_mov_b32 m0, s59
	v_lshl_add_u64 v[138:139], v[214:215], 0, s[24:25]
	ds_read_b128 v[160:163], v141 offset:49152
	ds_read_b128 v[164:167], v141 offset:50176
	ds_read_b128 v[168:171], v141 offset:51200
	ds_read_b128 v[172:175], v141 offset:52224
	ds_read_b128 v[176:179], v141 offset:53248
	ds_read_b128 v[180:183], v141 offset:54272
	ds_read_b128 v[186:189], v141 offset:55296
	ds_read_b128 v[194:197], v141 offset:56320
	global_load_lds_dwordx4 v[138:139], off
	v_lshl_add_u64 v[138:139], v[216:217], 0, s[24:25]
	s_mov_b32 m0, s60
	s_nop 0
	global_load_lds_dwordx4 v[138:139], off
	s_waitcnt vmcnt(6) lgkmcnt(0)
	s_barrier
	s_cbranch_vccnz .Lmskip_94_6
	v_mfma_f32_16x16x32_bf16 v[60:63], v[144:147], v[160:163], v[60:63]
	v_mfma_f32_16x16x32_bf16 v[56:59], v[152:155], v[160:163], v[56:59]
	v_mfma_f32_16x16x32_bf16 v[52:55], v[144:147], v[168:171], v[52:55]
	v_mfma_f32_16x16x32_bf16 v[48:51], v[152:155], v[168:171], v[48:51]
	v_mfma_f32_16x16x32_bf16 v[44:47], v[144:147], v[176:179], v[44:47]
	v_mfma_f32_16x16x32_bf16 v[40:43], v[152:155], v[176:179], v[40:43]
	v_mfma_f32_16x16x32_bf16 v[36:39], v[144:147], v[186:189], v[36:39]
	v_mfma_f32_16x16x32_bf16 v[32:35], v[152:155], v[186:189], v[32:35]
	v_mfma_f32_16x16x32_bf16 v[60:63], v[148:151], v[164:167], v[60:63]
	v_mfma_f32_16x16x32_bf16 v[56:59], v[156:159], v[164:167], v[56:59]
	v_mfma_f32_16x16x32_bf16 v[52:55], v[148:151], v[172:175], v[52:55]
	v_mfma_f32_16x16x32_bf16 v[48:51], v[156:159], v[172:175], v[48:51]
	v_mfma_f32_16x16x32_bf16 v[44:47], v[148:151], v[180:183], v[44:47]
	v_mfma_f32_16x16x32_bf16 v[40:43], v[156:159], v[180:183], v[40:43]
	v_mfma_f32_16x16x32_bf16 v[36:39], v[148:151], v[194:197], v[36:39]
	v_mfma_f32_16x16x32_bf16 v[32:35], v[156:159], v[194:197], v[32:35]
	v_mfma_f32_16x16x32_bf16 v[28:31], v[198:201], v[160:163], v[28:31]
	v_mfma_f32_16x16x32_bf16 v[24:27], v[206:209], v[160:163], v[24:27]
	v_mfma_f32_16x16x32_bf16 v[20:23], v[198:201], v[168:171], v[20:23]
	v_mfma_f32_16x16x32_bf16 v[16:19], v[206:209], v[168:171], v[16:19]
	v_mfma_f32_16x16x32_bf16 v[12:15], v[198:201], v[176:179], v[12:15]
	v_mfma_f32_16x16x32_bf16 v[8:11], v[206:209], v[176:179], v[8:11]
	v_mfma_f32_16x16x32_bf16 v[4:7], v[198:201], v[186:189], v[4:7]
	v_mfma_f32_16x16x32_bf16 v[0:3], v[206:209], v[186:189], v[0:3]
	v_mfma_f32_16x16x32_bf16 v[28:31], v[202:205], v[164:167], v[28:31]
	v_mfma_f32_16x16x32_bf16 v[24:27], v[210:213], v[164:167], v[24:27]
	v_mfma_f32_16x16x32_bf16 v[20:23], v[202:205], v[172:175], v[20:23]
	v_mfma_f32_16x16x32_bf16 v[16:19], v[210:213], v[172:175], v[16:19]
	v_mfma_f32_16x16x32_bf16 v[12:15], v[202:205], v[180:183], v[12:15]
	v_mfma_f32_16x16x32_bf16 v[8:11], v[210:213], v[180:183], v[8:11]
	v_mfma_f32_16x16x32_bf16 v[4:7], v[202:205], v[194:197], v[4:7]
	v_mfma_f32_16x16x32_bf16 v[0:3], v[210:213], v[194:197], v[0:3]
.Lmskip_94_6:
	s_barrier
	s_mov_b32 m0, s61
	v_lshl_add_u64 v[138:139], v[230:231], 0, s[24:25]
	global_load_lds_dwordx4 v[138:139], off
	v_lshl_add_u64 v[138:139], v[232:233], 0, s[24:25]
	s_mov_b32 m0, s62
	s_nop 0
	global_load_lds_dwordx4 v[138:139], off
	s_add_u32 s30, s30, 0x100
	s_addc_u32 s31, s31, 0
	s_add_u32 s26, s26, 0x100
	s_addc_u32 s27, s27, 0
	s_cmp_ge_u32 s71, s54
	s_mov_b32 s34, s71
	s_cbranch_scc0 .LBB0_94
	v_lshl_add_u32 v138, s69, 8, v140
	s_cmp_eq_u32 s100, 2
	s_cselect_b32 vcc_lo, 0x80, 0
	s_nop 0
	v_add_u32_e32 v138, vcc_lo, v138
	v_lshl_or_b32 v144, s70, 8, v143
	v_ashrrev_i32_e32 v139, 31, v138
	v_readlane_b32 s4, v253, 16
	v_ashrrev_i32_e32 v145, 31, v144
	v_cvt_pk_bf16_f32 v124, v124, v125
	v_cvt_pk_bf16_f32 v125, v126, v127
	v_cvt_pk_bf16_f32 v126, v120, v121
	v_lshlrev_b64 v[120:121], 11, v[138:139]
	v_readlane_b32 s5, v253, 17
	v_cvt_pk_bf16_f32 v127, v122, v123
	v_lshlrev_b64 v[122:123], 1, v[144:145]
	v_cvt_pk_bf16_f32 v116, v116, v117
	v_cvt_pk_bf16_f32 v117, v118, v119
	v_cvt_pk_bf16_f32 v119, v114, v115
	s_nop 0
	v_lshl_add_u64 v[120:121], s[4:5], 0, v[120:121]
	v_lshl_add_u64 v[120:121], v[120:121], 0, v[122:123]
	global_store_dwordx4 v[120:121], v[124:127], off
	v_or_b32_e32 v114, 32, v138
	v_cvt_pk_bf16_f32 v108, v108, v109
	v_cvt_pk_bf16_f32 v109, v110, v111
	v_cvt_pk_bf16_f32 v111, v106, v107
	v_or_b32_e32 v106, 48, v138
	v_or_b32_e32 v124, 16, v138
	v_cvt_pk_bf16_f32 v68, v68, v69
	v_cvt_pk_bf16_f32 v69, v70, v71
	v_cvt_pk_bf16_f32 v70, v64, v65
	v_add_u32_e32 v64, 0x80, v138
	v_cvt_pk_bf16_f32 v60, v60, v61
	v_cvt_pk_bf16_f32 v61, v62, v63
	v_cvt_pk_bf16_f32 v63, v58, v59
	v_add_u32_e32 v58, 0x90, v138
	v_cvt_pk_bf16_f32 v52, v52, v53
	v_cvt_pk_bf16_f32 v53, v54, v55
	v_cvt_pk_bf16_f32 v55, v50, v51
	v_add_u32_e32 v50, 0xa0, v138
	v_cvt_pk_bf16_f32 v44, v44, v45
	v_cvt_pk_bf16_f32 v45, v46, v47
	v_cvt_pk_bf16_f32 v47, v42, v43
	v_add_u32_e32 v42, 0xb0, v138
	v_ashrrev_i32_e32 v125, 31, v124
	v_ashrrev_i32_e32 v115, 31, v114
	v_ashrrev_i32_e32 v107, 31, v106
	v_ashrrev_i32_e32 v65, 31, v64
	v_ashrrev_i32_e32 v59, 31, v58
	v_ashrrev_i32_e32 v51, 31, v50
	v_ashrrev_i32_e32 v43, 31, v42
	v_cvt_pk_bf16_f32 v118, v112, v113
	v_lshlrev_b64 v[112:113], 11, v[124:125]
	v_cvt_pk_bf16_f32 v110, v104, v105
	v_lshlrev_b64 v[104:105], 11, v[114:115]
	v_cvt_pk_bf16_f32 v100, v100, v101
	v_cvt_pk_bf16_f32 v101, v102, v103
	v_cvt_pk_bf16_f32 v102, v96, v97
	v_lshlrev_b64 v[96:97], 11, v[106:107]
	v_cvt_pk_bf16_f32 v62, v56, v57
	v_lshlrev_b64 v[56:57], 11, v[64:65]
	v_cvt_pk_bf16_f32 v54, v48, v49
	v_lshlrev_b64 v[48:49], 11, v[58:59]
	v_cvt_pk_bf16_f32 v46, v40, v41
	v_lshlrev_b64 v[40:41], 11, v[50:51]
	v_cvt_pk_bf16_f32 v36, v36, v37
	v_cvt_pk_bf16_f32 v37, v38, v39
	v_cvt_pk_bf16_f32 v38, v32, v33
	v_lshlrev_b64 v[32:33], 11, v[42:43]
	v_lshl_add_u64 v[112:113], s[4:5], 0, v[112:113]
	v_lshl_add_u64 v[104:105], s[4:5], 0, v[104:105]
	v_lshl_add_u64 v[96:97], s[4:5], 0, v[96:97]
	v_lshl_add_u64 v[56:57], s[4:5], 0, v[56:57]
	v_lshl_add_u64 v[48:49], s[4:5], 0, v[48:49]
	v_lshl_add_u64 v[40:41], s[4:5], 0, v[40:41]
	v_lshl_add_u64 v[32:33], s[4:5], 0, v[32:33]
	v_lshl_add_u64 v[112:113], v[112:113], 0, v[122:123]
	v_lshl_add_u64 v[104:105], v[104:105], 0, v[122:123]
	v_lshl_add_u64 v[96:97], v[96:97], 0, v[122:123]
	v_lshl_add_u64 v[56:57], v[56:57], 0, v[122:123]
	v_lshl_add_u64 v[48:49], v[48:49], 0, v[122:123]
	v_lshl_add_u64 v[40:41], v[40:41], 0, v[122:123]
	v_lshl_add_u64 v[32:33], v[32:33], 0, v[122:123]
	s_and_b64 vcc, exec, s[22:23]
	s_mov_b32 s70, s65
	s_mov_b32 s69, s68
	s_mov_b64 s[34:35], s[0:1]
	s_mov_b64 s[30:31], s[28:29]
	s_mov_b32 s71, 0x42ce8ed0
	v_readlane_b32 s6, v253, 18
	v_readlane_b32 s7, v253, 19
	v_readlane_b32 s8, v253, 20
	v_readlane_b32 s9, v253, 21
	v_readlane_b32 s10, v253, 22
	v_readlane_b32 s11, v253, 23
	v_readlane_b32 s12, v253, 24
	v_readlane_b32 s13, v253, 25
	v_readlane_b32 s14, v253, 26
	v_readlane_b32 s15, v253, 27
	v_readlane_b32 s16, v253, 28
	v_readlane_b32 s17, v253, 29
	v_readlane_b32 s18, v253, 30
	v_readlane_b32 s19, v253, 31
	global_store_dwordx4 v[112:113], v[116:119], off
	global_store_dwordx4 v[104:105], v[108:111], off
	v_cvt_pk_bf16_f32 v103, v98, v99
	global_store_dwordx4 v[96:97], v[100:103], off
	v_cvt_pk_bf16_f32 v92, v92, v93
	v_cvt_pk_bf16_f32 v93, v94, v95
	v_cvt_pk_bf16_f32 v94, v88, v89
	v_cvt_pk_bf16_f32 v95, v90, v91
	global_store_dwordx4 v[120:121], v[92:95], off offset:256
	v_cvt_pk_bf16_f32 v84, v84, v85
	v_cvt_pk_bf16_f32 v85, v86, v87
	v_cvt_pk_bf16_f32 v86, v80, v81
	v_cvt_pk_bf16_f32 v87, v82, v83
	global_store_dwordx4 v[112:113], v[84:87], off offset:256
	v_cvt_pk_bf16_f32 v76, v76, v77
	v_cvt_pk_bf16_f32 v77, v78, v79
	v_cvt_pk_bf16_f32 v78, v72, v73
	v_cvt_pk_bf16_f32 v79, v74, v75
	global_store_dwordx4 v[104:105], v[76:79], off offset:256
	v_cvt_pk_bf16_f32 v71, v66, v67
	global_store_dwordx4 v[96:97], v[68:71], off offset:256
	s_cmp_lg_u32 s100, 0
	s_cbranch_scc1 .Lpjh_nost
	global_store_dwordx4 v[56:57], v[60:63], off
	global_store_dwordx4 v[48:49], v[52:55], off
	global_store_dwordx4 v[40:41], v[44:47], off
	v_cvt_pk_bf16_f32 v39, v34, v35
	global_store_dwordx4 v[32:33], v[36:39], off
	v_cvt_pk_bf16_f32 v28, v28, v29
	v_cvt_pk_bf16_f32 v29, v30, v31
	v_cvt_pk_bf16_f32 v30, v24, v25
	v_cvt_pk_bf16_f32 v31, v26, v27
	global_store_dwordx4 v[56:57], v[28:31], off offset:256
	v_cvt_pk_bf16_f32 v20, v20, v21
	v_cvt_pk_bf16_f32 v21, v22, v23
	v_cvt_pk_bf16_f32 v22, v16, v17
	v_cvt_pk_bf16_f32 v23, v18, v19
	global_store_dwordx4 v[48:49], v[20:23], off offset:256
	v_cvt_pk_bf16_f32 v12, v12, v13
	v_cvt_pk_bf16_f32 v13, v14, v15
	v_cvt_pk_bf16_f32 v14, v8, v9
	v_cvt_pk_bf16_f32 v15, v10, v11
	global_store_dwordx4 v[40:41], v[12:15], off offset:256
	v_cvt_pk_bf16_f32 v4, v4, v5
	v_cvt_pk_bf16_f32 v5, v6, v7
	v_cvt_pk_bf16_f32 v6, v0, v1
	v_cvt_pk_bf16_f32 v7, v2, v3
	global_store_dwordx4 v[32:33], v[4:7], off offset:256
